# sgu: bias loads hoisted to the top of the MFMA section, LN stats 16 loads in one batch
# baseline (speedup 1.0000x reference)
.LBB0_266:
	v_add_u32_e32 v226, s31, v125
	v_ashrrev_i32_e32 v227, 31, v226
	v_lshl_add_u64 v[226:227], v[226:227], 2, s[18:19]
	global_load_dword v234, v[226:227], off
	v_add_u32_e32 v228, s31, v124
	v_ashrrev_i32_e32 v229, 31, v228
	v_lshl_add_u64 v[228:229], v[228:229], 2, s[18:19]
	global_load_dword v235, v[228:229], off
	v_add_u32_e32 v230, s31, v51
	v_ashrrev_i32_e32 v231, 31, v230
	v_lshl_add_u64 v[230:231], v[230:231], 2, s[18:19]
	global_load_dword v236, v[230:231], off
	v_add_u32_e32 v232, s31, v50
	v_ashrrev_i32_e32 v233, 31, v232
	v_lshl_add_u64 v[232:233], v[232:233], 2, s[18:19]
	global_load_dword v237, v[232:233], off
	v_cvt_pk_bf16_f32 v20, v24, v25
	ds_write_b16 v102, v20 offset:34816
	ds_write_b16_d16_hi v102, v20 offset:35088
	v_cvt_pk_bf16_f32 v20, v26, v27
	v_cvt_pk_bf16_f32 v16, v16, v17
	ds_write_b16 v102, v20 offset:35360
	ds_write_b16_d16_hi v102, v20 offset:35632
	ds_write_b16 v102, v16 offset:35904
	ds_write_b16_d16_hi v102, v16 offset:36176
	v_cvt_pk_bf16_f32 v16, v18, v19
	ds_write_b16 v102, v16 offset:36448
	ds_write_b16_d16_hi v102, v16 offset:36720
	s_waitcnt lgkmcnt(0)
	s_barrier
	ds_read_b128 v[16:19], v119
	ds_read_b128 v[20:23], v119 offset:4352
	ds_read_b128 v[24:27], v119 offset:8704
	ds_read_b128 v[28:31], v119 offset:13056
	ds_read_b128 v[32:35], v120 offset:34816
	ds_read_b128 v[36:39], v120 offset:35904
	s_waitcnt lgkmcnt(1)
	v_mfma_f32_16x16x32_bf16 v[40:43], v[32:35], v[16:19], 0
	v_add_u32_e32 v56, s31, v125
	v_ashrrev_i32_e32 v57, 31, v56
	v_lshl_add_u64 v[56:57], v[56:57], 2, s[18:19]
	s_waitcnt lgkmcnt(0)
	v_mfma_f32_16x16x32_bf16 v[16:19], v[36:39], v[16:19], 0
	v_or_b32_e32 v48, s31, v63
	v_lshlrev_b32_e32 v144, 1, v48
	v_lshl_add_u64 v[48:49], s[26:27], 0, v[144:145]
	v_mfma_f32_16x16x32_bf16 v[44:47], v[32:35], v[20:23], 0
	s_add_i32 s30, s30, s38
	s_cmpk_lt_i32 s30, 0x440
	v_mfma_f32_16x16x32_bf16 v[20:23], v[36:39], v[20:23], 0
	v_mfma_f32_16x16x32_bf16 v[126:129], v[32:35], v[24:27], 0
	v_mfma_f32_16x16x32_bf16 v[24:27], v[36:39], v[24:27], 0
	v_mfma_f32_16x16x32_bf16 v[32:35], v[32:35], v[28:31], 0
	v_mfma_f32_16x16x32_bf16 v[28:31], v[36:39], v[28:31], 0
	ds_read_b128 v[36:39], v119 offset:64
	ds_read_b128 v[130:133], v119 offset:4416
	ds_read_b128 v[134:137], v119 offset:8768
	ds_read_b128 v[138:141], v119 offset:13120
	ds_read_b128 v[162:165], v121 offset:34816
	ds_read_b128 v[166:169], v121 offset:35904
	s_waitcnt lgkmcnt(1)
	v_mfma_f32_16x16x32_bf16 v[40:43], v[162:165], v[36:39], v[40:43]
	s_waitcnt lgkmcnt(0)
	v_mfma_f32_16x16x32_bf16 v[16:19], v[166:169], v[36:39], v[16:19]
	v_mfma_f32_16x16x32_bf16 v[36:39], v[162:165], v[130:133], v[44:47]
	v_mfma_f32_16x16x32_bf16 v[20:23], v[166:169], v[130:133], v[20:23]
	v_mfma_f32_16x16x32_bf16 v[44:47], v[162:165], v[134:137], v[126:129]
	v_mfma_f32_16x16x32_bf16 v[24:27], v[166:169], v[134:137], v[24:27]
	v_mfma_f32_16x16x32_bf16 v[32:35], v[162:165], v[138:141], v[32:35]
	v_mfma_f32_16x16x32_bf16 v[28:31], v[166:169], v[138:141], v[28:31]
	ds_read_b128 v[126:129], v119 offset:128
	ds_read_b128 v[130:133], v119 offset:4480
	ds_read_b128 v[134:137], v119 offset:8832
	ds_read_b128 v[138:141], v119 offset:13184
	ds_read_b128 v[162:165], v122 offset:34816
	ds_read_b128 v[166:169], v122 offset:35904
	s_waitcnt lgkmcnt(1)
	v_mfma_f32_16x16x32_bf16 v[40:43], v[162:165], v[126:129], v[40:43]
	s_waitcnt lgkmcnt(0)
	v_mfma_f32_16x16x32_bf16 v[16:19], v[166:169], v[126:129], v[16:19]
	v_mfma_f32_16x16x32_bf16 v[36:39], v[162:165], v[130:133], v[36:39]
	v_mfma_f32_16x16x32_bf16 v[20:23], v[166:169], v[130:133], v[20:23]
	v_mfma_f32_16x16x32_bf16 v[126:129], v[162:165], v[134:137], v[44:47]
	v_mfma_f32_16x16x32_bf16 v[24:27], v[166:169], v[134:137], v[24:27]
	v_mfma_f32_16x16x32_bf16 v[130:133], v[162:165], v[138:141], v[32:35]
	v_mfma_f32_16x16x32_bf16 v[134:137], v[166:169], v[138:141], v[28:31]
	s_nop 2
	ds_read_b128 v[28:31], v119 offset:192
	ds_read_b128 v[32:35], v119 offset:4544
	ds_read_b128 v[138:141], v119 offset:8896
	ds_read_b128 v[162:165], v119 offset:13248
	ds_read_b128 v[166:169], v123 offset:34816
	ds_read_b128 v[170:173], v123 offset:35904
	v_mov_b32_e32 v56, v234
	s_waitcnt lgkmcnt(1)
	v_mfma_f32_16x16x32_bf16 v[44:47], v[166:169], v[28:31], v[40:43]
	s_waitcnt lgkmcnt(0)
	v_mfma_f32_16x16x32_bf16 v[40:43], v[170:173], v[28:31], v[16:19]
	s_waitcnt vmcnt(0)
	s_nop 4
	v_pk_add_f32 v[44:45], v[44:45], v[56:57] op_sel_hi:[1,0]
	v_mfma_f32_16x16x32_bf16 v[28:31], v[166:169], v[138:141], v[126:129]
	v_add_f32_e64 v40, v40, v56
	v_add_f32_e64 v41, v41, v56
	v_pk_add_f32 v[42:43], v[42:43], v[56:57] op_sel_hi:[1,0]
	v_pk_add_f32 v[46:47], v[46:47], v[56:57] op_sel_hi:[1,0]
	v_lshlrev_b32_e32 v128, 16, v14
	v_and_b32_e32 v129, 0xffff0000, v14
	v_lshlrev_b32_e32 v14, 16, v15
	v_and_b32_e32 v15, 0xffff0000, v15
	v_lshlrev_b32_e32 v126, 16, v12
	v_and_b32_e32 v127, 0xffff0000, v12
	v_lshlrev_b32_e32 v12, 16, v13
	v_and_b32_e32 v13, 0xffff0000, v13
	v_pk_mul_f32 v[42:43], v[42:43], v[14:15]
	v_pk_mul_f32 v[14:15], v[40:41], v[128:129]
	v_lshlrev_b64 v[40:41], 12, v[54:55]
	v_pk_mul_f32 v[46:47], v[46:47], v[12:13]
	v_pk_mul_f32 v[12:13], v[44:45], v[126:127]
	v_cvt_pk_bf16_f32 v14, v14, v15
	v_lshl_add_u64 v[40:41], v[48:49], 0, v[40:41]
	v_cvt_pk_bf16_f32 v12, v12, v13
	v_cvt_pk_bf16_f32 v13, v46, v47
	v_cvt_pk_bf16_f32 v15, v42, v43
	global_store_dwordx4 v[40:41], v[12:15], off
	v_mfma_f32_16x16x32_bf16 v[36:39], v[166:169], v[32:35], v[36:39]
	v_lshlrev_b32_e32 v42, 16, v10
	v_add_u32_e32 v14, s31, v124
	v_ashrrev_i32_e32 v15, 31, v14
	v_lshl_add_u64 v[14:15], v[14:15], 2, s[18:19]
	v_mov_b32_e32 v14, v235
	v_mfma_f32_16x16x32_bf16 v[32:35], v[170:173], v[32:35], v[20:23]
	v_add_u32_e32 v12, s34, v103
	v_and_b32_e32 v43, 0xffff0000, v10
	v_lshlrev_b32_e32 v10, 16, v11
	v_and_b32_e32 v11, 0xffff0000, v11
	v_ashrrev_i32_e32 v13, 31, v12
	v_lshlrev_b32_e32 v40, 16, v8
	v_and_b32_e32 v41, 0xffff0000, v8
	v_lshlrev_b32_e32 v8, 16, v9
	v_and_b32_e32 v9, 0xffff0000, v9
	v_lshlrev_b64 v[12:13], 12, v[12:13]
	v_lshl_add_u64 v[12:13], v[48:49], 0, v[12:13]
	v_mfma_f32_16x16x32_bf16 v[24:27], v[170:173], v[138:141], v[24:27]
	s_waitcnt vmcnt(0)
	v_pk_add_f32 v[36:37], v[36:37], v[14:15] op_sel_hi:[1,0]
	v_pk_add_f32 v[38:39], v[38:39], v[14:15] op_sel_hi:[1,0]
	v_pk_add_f32 v[32:33], v[32:33], v[14:15] op_sel_hi:[1,0]
	v_pk_add_f32 v[14:15], v[34:35], v[14:15] op_sel_hi:[1,0]
	v_pk_mul_f32 v[38:39], v[38:39], v[8:9]
	v_pk_mul_f32 v[14:15], v[14:15], v[10:11]
	v_pk_mul_f32 v[10:11], v[32:33], v[42:43]
	v_pk_mul_f32 v[8:9], v[36:37], v[40:41]
	v_cvt_pk_bf16_f32 v10, v10, v11
	v_cvt_pk_bf16_f32 v11, v14, v15
	v_lshlrev_b32_e32 v14, 16, v6
	v_cvt_pk_bf16_f32 v8, v8, v9
	v_cvt_pk_bf16_f32 v9, v38, v39
	global_store_dwordx4 v[12:13], v[8:11], off
	v_lshlrev_b32_e32 v12, 16, v4
	v_and_b32_e32 v13, 0xffff0000, v4
	v_add_u32_e32 v10, s31, v51
	v_ashrrev_i32_e32 v11, 31, v10
	v_lshl_add_u64 v[10:11], v[10:11], 2, s[18:19]
	v_mov_b32_e32 v10, v236
	v_add_u32_e32 v8, s34, v104
	v_lshlrev_b32_e32 v4, 16, v5
	v_and_b32_e32 v5, 0xffff0000, v5
	v_and_b32_e32 v15, 0xffff0000, v6
	v_lshlrev_b32_e32 v6, 16, v7
	v_and_b32_e32 v7, 0xffff0000, v7
	v_ashrrev_i32_e32 v9, 31, v8
	v_lshlrev_b64 v[8:9], 12, v[8:9]
	v_lshl_add_u64 v[8:9], v[48:49], 0, v[8:9]
	v_mfma_f32_16x16x32_bf16 v[20:23], v[166:169], v[162:165], v[130:133]
	s_waitcnt vmcnt(0)
	v_pk_add_f32 v[28:29], v[28:29], v[10:11] op_sel_hi:[1,0]
	v_pk_add_f32 v[30:31], v[30:31], v[10:11] op_sel_hi:[1,0]
	v_mfma_f32_16x16x32_bf16 v[16:19], v[170:173], v[162:165], v[134:137]
	v_mul_f32_e64 v30, v30, v4
	v_mul_f32_e64 v31, v31, v5
	v_pk_mul_f32 v[4:5], v[28:29], v[12:13]
	v_pk_add_f32 v[12:13], v[24:25], v[10:11] op_sel_hi:[1,0]
	v_pk_add_f32 v[10:11], v[26:27], v[10:11] op_sel_hi:[1,0]
	v_cvt_pk_bf16_f32 v4, v4, v5
	v_cvt_pk_bf16_f32 v5, v30, v31
	s_nop 0
	v_pk_mul_f32 v[10:11], v[10:11], v[6:7]
	v_pk_mul_f32 v[6:7], v[12:13], v[14:15]
	s_nop 0
	v_cvt_pk_bf16_f32 v6, v6, v7
	v_cvt_pk_bf16_f32 v7, v10, v11
	global_store_dwordx4 v[8:9], v[4:7], off
	v_lshlrev_b32_e32 v8, 16, v0
	v_and_b32_e32 v9, 0xffff0000, v0
	v_add_u32_e32 v6, s31, v50
	v_ashrrev_i32_e32 v7, 31, v6
	v_lshl_add_u64 v[6:7], v[6:7], 2, s[18:19]
	v_mov_b32_e32 v6, v237
	v_add_u32_e32 v4, s34, v105
	v_lshlrev_b32_e32 v0, 16, v1
	v_and_b32_e32 v1, 0xffff0000, v1
	v_ashrrev_i32_e32 v5, 31, v4
	v_lshlrev_b32_e32 v10, 16, v2
	v_and_b32_e32 v11, 0xffff0000, v2
	v_lshlrev_b32_e32 v2, 16, v3
	v_and_b32_e32 v3, 0xffff0000, v3
	v_lshlrev_b64 v[4:5], 12, v[4:5]
	v_lshl_add_u64 v[4:5], v[48:49], 0, v[4:5]
	s_waitcnt vmcnt(0)
	v_pk_add_f32 v[12:13], v[20:21], v[6:7] op_sel_hi:[1,0]
	v_pk_add_f32 v[14:15], v[22:23], v[6:7] op_sel_hi:[1,0]
	s_nop 0
	v_pk_mul_f32 v[14:15], v[14:15], v[0:1]
	v_pk_mul_f32 v[0:1], v[12:13], v[8:9]
	v_pk_add_f32 v[8:9], v[16:17], v[6:7] op_sel_hi:[1,0]
	v_pk_add_f32 v[6:7], v[18:19], v[6:7] op_sel_hi:[1,0]
	v_cvt_pk_bf16_f32 v0, v0, v1
	v_cvt_pk_bf16_f32 v1, v14, v15
	s_nop 0
	v_pk_mul_f32 v[6:7], v[6:7], v[2:3]
	v_pk_mul_f32 v[2:3], v[8:9], v[10:11]
	s_nop 0
	v_cvt_pk_bf16_f32 v2, v2, v3
	v_cvt_pk_bf16_f32 v3, v6, v7
	global_store_dwordx4 v[4:5], v[0:3], off
	s_cbranch_scc0 .LBB0_277
.LBB0_267:
	s_ashr_i32 s36, s30, 4
	s_and_b32 s35, s30, 15
	s_lshl_b32 s34, s36, 7
	s_lshl_b32 s31, s35, 7
	v_add_u32_e32 v0, s34, v61
	v_or_b32_e32 v4, s31, v60
	v_ashrrev_i32_e32 v1, 31, v0
	v_lshlrev_b32_e32 v56, 2, v4
	v_lshlrev_b64 v[2:3], 13, v[0:1]
	v_lshlrev_b32_e32 v144, 1, v4
	v_or_b32_e32 v4, 4, v0
	v_lshl_add_u64 v[2:3], s[8:9], 0, v[2:3]
	v_ashrrev_i32_e32 v5, 31, v4
	v_lshl_add_u64 v[2:3], v[2:3], 0, v[144:145]
	v_lshlrev_b64 v[4:5], 13, v[4:5]
	v_add_co_u32_e32 v2, vcc, s53, v2
	v_lshl_add_u64 v[4:5], s[8:9], 0, v[4:5]
	s_nop 0
	v_addc_co_u32_e32 v3, vcc, 0, v3, vcc
	v_lshl_add_u64 v[4:5], v[4:5], 0, v[144:145]
	v_add_co_u32_e32 v4, vcc, s53, v4
	s_waitcnt lgkmcnt(0)
	global_load_dwordx4 v[16:19], v56, s[12:13] offset:16
	global_load_dwordx4 v[20:23], v56, s[14:15] offset:16
	global_load_dwordx4 v[24:27], v56, s[12:13]
	global_load_dwordx4 v[28:31], v56, s[14:15]
	v_addc_co_u32_e32 v5, vcc, 0, v5, vcc
	global_load_dwordx4 v[44:47], v[2:3], off
	global_load_dwordx4 v[40:43], v[4:5], off
	v_or_b32_e32 v2, 8, v0
	v_ashrrev_i32_e32 v3, 31, v2
	v_lshlrev_b64 v[2:3], 13, v[2:3]
	v_or_b32_e32 v0, 12, v0
	v_lshl_add_u64 v[2:3], s[8:9], 0, v[2:3]
	v_ashrrev_i32_e32 v1, 31, v0
	v_lshl_add_u64 v[2:3], v[2:3], 0, v[144:145]
	v_lshlrev_b64 v[0:1], 13, v[0:1]
	v_add_co_u32_e32 v2, vcc, s53, v2
	v_lshl_add_u64 v[0:1], s[8:9], 0, v[0:1]
	s_nop 0
	v_addc_co_u32_e32 v3, vcc, 0, v3, vcc
	v_lshl_add_u64 v[0:1], v[0:1], 0, v[144:145]
	v_add_u32_e32 v54, s34, v62
	v_add_co_u32_e32 v0, vcc, s53, v0
	v_or_b32_e32 v4, 16, v54
	s_nop 0
	v_addc_co_u32_e32 v1, vcc, 0, v1, vcc
	s_lshl_b32 s76, s35, 8
	v_ashrrev_i32_e32 v55, 31, v54
	v_ashrrev_i32_e32 v5, 31, v4
	global_load_dwordx4 v[36:39], v[2:3], off
	global_load_dwordx4 v[32:35], v[0:1], off
	v_lshl_add_u64 v[0:1], v[52:53], 0, s[76:77]
	v_lshlrev_b64 v[2:3], 13, v[54:55]
	v_lshlrev_b64 v[4:5], 13, v[4:5]
	v_lshl_add_u64 v[2:3], v[0:1], 0, v[2:3]
	v_lshl_add_u64 v[4:5], v[0:1], 0, v[4:5]
	global_load_dwordx4 v[12:15], v[2:3], off
	global_load_dwordx4 v[8:11], v[4:5], off
	v_or_b32_e32 v2, 32, v54
	v_or_b32_e32 v4, 48, v54
	v_ashrrev_i32_e32 v3, 31, v2
	v_ashrrev_i32_e32 v5, 31, v4
	v_lshlrev_b64 v[2:3], 13, v[2:3]
	v_lshlrev_b64 v[4:5], 13, v[4:5]
	v_lshl_add_u64 v[2:3], v[0:1], 0, v[2:3]
	v_lshl_add_u64 v[0:1], v[0:1], 0, v[4:5]
	global_load_dwordx4 v[4:7], v[2:3], off
	s_nop 0
	global_load_dwordx4 v[0:3], v[0:1], off
	s_barrier
	s_and_saveexec_b64 s[10:11], s[4:5]
	s_cbranch_execz .LBB0_269
	v_add_u32_e32 v48, s34, v58
	v_ashrrev_i32_e32 v49, 31, v48
	v_lshlrev_b64 v[48:49], 8, v[48:49]
	v_lshl_add_u64 v[48:49], s[24:25], 0, v[48:49]
	s_mov_b32 s6, 0x3a000000
	global_load_dwordx4 v[124:127], v[48:49], off
	global_load_dwordx4 v[128:131], v[48:49], off offset:16
	global_load_dwordx4 v[132:135], v[48:49], off offset:32
	global_load_dwordx4 v[136:139], v[48:49], off offset:48
	global_load_dwordx4 v[226:229], v[48:49], off offset:64
	global_load_dwordx4 v[230:233], v[48:49], off offset:80
	global_load_dwordx4 v[234:237], v[48:49], off offset:96
	global_load_dwordx4 v[238:241], v[48:49], off offset:112
	global_load_dwordx4 v[194:197], v[48:49], off offset:128
	global_load_dwordx4 v[198:201], v[48:49], off offset:144
	global_load_dwordx4 v[202:205], v[48:49], off offset:160
	global_load_dwordx4 v[206:209], v[48:49], off offset:176
	global_load_dwordx4 v[210:213], v[48:49], off offset:192
	global_load_dwordx4 v[214:217], v[48:49], off offset:208
	global_load_dwordx4 v[218:221], v[48:49], off offset:224
	global_load_dwordx4 v[222:225], v[48:49], off offset:240
	s_waitcnt vmcnt(15)
	v_add_f32_e32 v50, v124, v126
	v_add_f32_e32 v51, v125, v127
	s_waitcnt vmcnt(14)
	v_add_f32_e32 v57, v128, v130
	v_add_f32_e32 v50, v50, v57
	v_add_f32_e32 v57, v129, v131
	v_add_f32_e32 v51, v51, v57
	s_waitcnt vmcnt(13)
	v_add_f32_e32 v57, v132, v134
	v_add_f32_e32 v50, v50, v57
	v_add_f32_e32 v57, v133, v135
	v_add_f32_e32 v51, v51, v57
	s_waitcnt vmcnt(12)
	v_add_f32_e32 v57, v136, v138
	v_add_f32_e32 v50, v50, v57
	v_add_f32_e32 v57, v137, v139
	v_add_f32_e32 v51, v51, v57
	s_waitcnt vmcnt(11)
	v_add_f32_e32 v57, v226, v228
	v_add_f32_e32 v50, v50, v57
	v_add_f32_e32 v57, v227, v229
	v_add_f32_e32 v51, v51, v57
	s_waitcnt vmcnt(10)
	v_add_f32_e32 v57, v230, v232
	v_add_f32_e32 v50, v50, v57
	v_add_f32_e32 v57, v231, v233
	v_add_f32_e32 v51, v51, v57
	s_waitcnt vmcnt(9)
	v_add_f32_e32 v57, v234, v236
	v_add_f32_e32 v50, v50, v57
	v_add_f32_e32 v57, v235, v237
	v_add_f32_e32 v51, v51, v57
	s_waitcnt vmcnt(8)
	v_add_f32_e32 v57, v238, v240
	v_add_f32_e32 v50, v50, v57
	v_add_f32_e32 v57, v239, v241
	v_add_f32_e32 v51, v51, v57
	s_waitcnt vmcnt(7)
	v_add_f32_e32 v57, v194, v196
	v_add_f32_e32 v50, v50, v57
	v_add_f32_e32 v57, v195, v197
	v_add_f32_e32 v51, v51, v57
	s_waitcnt vmcnt(6)
	v_add_f32_e32 v57, v198, v200
	v_add_f32_e32 v50, v50, v57
	v_add_f32_e32 v57, v199, v201
	v_add_f32_e32 v51, v51, v57
	s_waitcnt vmcnt(5)
	v_add_f32_e32 v57, v202, v204
	v_add_f32_e32 v50, v50, v57
	v_add_f32_e32 v57, v203, v205
	v_add_f32_e32 v51, v51, v57
	s_waitcnt vmcnt(4)
	v_add_f32_e32 v57, v206, v208
	v_add_f32_e32 v50, v50, v57
	v_add_f32_e32 v57, v207, v209
	v_add_f32_e32 v51, v51, v57
	s_waitcnt vmcnt(3)
	v_add_f32_e32 v57, v210, v212
	v_add_f32_e32 v50, v50, v57
	v_add_f32_e32 v57, v211, v213
	v_add_f32_e32 v51, v51, v57
	s_waitcnt vmcnt(2)
	v_add_f32_e32 v57, v214, v216
	v_add_f32_e32 v50, v50, v57
	v_add_f32_e32 v57, v215, v217
	v_add_f32_e32 v51, v51, v57
	s_waitcnt vmcnt(1)
	v_add_f32_e32 v57, v218, v220
	v_add_f32_e32 v50, v50, v57
	v_add_f32_e32 v57, v219, v221
	v_add_f32_e32 v51, v51, v57
	s_waitcnt vmcnt(0)
	v_add_f32_e32 v57, v222, v224
	v_add_f32_e32 v50, v50, v57
	v_add_f32_e32 v57, v223, v225
	v_add_f32_e32 v51, v51, v57
	v_mul_f32_e32 v48, 0x3a000000, v50
	v_mov_b32_e32 v49, v51
	v_mul_f32_e32 v50, v48, v48
	v_fma_f32 v49, v49, s6, -v50
	v_max_f32_e32 v49, 0, v49
	v_add_f32_e32 v49, 0x358637bd, v49
	v_cmp_gt_f32_e32 vcc, s59, v49
	v_mul_f32_e32 v50, 0x4f800000, v49
	s_nop 0
	v_cndmask_b32_e32 v49, v49, v50, vcc
	v_sqrt_f32_e32 v50, v49
	s_nop 0
	v_add_u32_e32 v51, -1, v50
	v_fma_f32 v57, -v51, v50, v49
	v_cmp_ge_f32_e64 s[6:7], 0, v57
	v_add_u32_e32 v57, 1, v50
	s_nop 0
	v_cndmask_b32_e64 v51, v50, v51, s[6:7]
	v_fma_f32 v50, -v57, v50, v49
	v_cmp_lt_f32_e64 s[6:7], 0, v50
	s_nop 1
	v_cndmask_b32_e64 v50, v51, v57, s[6:7]
	v_mul_f32_e32 v51, 0x37800000, v50
	v_cndmask_b32_e32 v50, v50, v51, vcc
	v_cmp_class_f32_e32 vcc, v49, v187
	s_nop 1
	v_cndmask_b32_e32 v49, v50, v49, vcc
	v_div_scale_f32 v50, s[6:7], v49, v49, 1.0
	v_rcp_f32_e32 v51, v50
	s_nop 0
	v_fma_f32 v57, -v50, v51, 1.0
	v_fmac_f32_e32 v51, v57, v51
	v_div_scale_f32 v57, vcc, 1.0, v49, 1.0
	v_mul_f32_e32 v124, v57, v51
	v_fma_f32 v125, -v50, v124, v57
	v_fmac_f32_e32 v124, v125, v51
	v_fma_f32 v50, -v50, v124, v57
	v_div_fmas_f32 v50, v50, v51, v124
	v_div_fixup_f32 v49, v50, v49, 1.0
	ds_write_b64 v106, v[48:49]
